# E4 + MLA loop: drop redundant m0 save and restore around LDS-DMA, shorten the no-rescale softmax branch chain
# speedup vs baseline: 1.0077x; 1.0055x over previous
.LBB0_828:
	s_sub_i32 s50, s82, 64
	s_cmp_lt_u32 s3, 0x100
	s_cbranch_scc1 .Lmla_dma1_skip
	s_lshl_b64 s[14:15], s[50:51], 13
	s_add_u32 s44, s80, s14
	s_addc_u32 s45, s81, s15
	s_add_u32 s14, s78, s14
	s_addc_u32 s15, s79, s15
	s_cmp_lg_u32 0, -1
	s_cselect_b32 s16, 0, 0
	s_add_i32 s16, s16, s41
	v_lshl_add_u64 v[80:81], s[44:45], 0, v[128:129]
	s_add_i32 s23, s16, 0x4000
	s_mov_b32 m0, s23
	s_nop 0
	global_load_lds_dwordx4 v[80:81], off
	v_lshl_add_u64 v[80:81], s[44:45], 0, v[192:193]
	s_add_i32 s23, s16, 0x6000
	s_mov_b32 m0, s23
	s_nop 0
	global_load_lds_dwordx4 v[80:81], off
	v_lshl_add_u64 v[80:81], s[14:15], 0, v[190:191]
	s_add_i32 s23, s16, 0xc000
	s_mov_b32 m0, s23
	s_nop 0
	global_load_lds_dwordx4 v[80:81], off
	v_lshl_add_u64 v[80:81], s[14:15], 0, v[188:189]
	s_add_i32 s14, s16, 0xe000
	s_mov_b32 m0, s14
	s_nop 0
	global_load_lds_dwordx4 v[80:81], off
	s_lshl_b64 s[14:15], s[50:51], 7
	v_lshl_add_u64 v[80:81], v[194:195], 0, s[14:15]
	s_add_i32 s16, s16, 0x12800
	s_mov_b32 m0, s16
	s_nop 0
	global_load_lds_dwordx4 v[80:81], off
	s_lshl_b64 s[14:15], s[50:51], 13
	s_add_u32 s44, s80, s14
	s_addc_u32 s45, s81, s15
	s_add_u32 s14, s78, s14
	s_addc_u32 s15, s79, s15
	s_sub_u32 s44, s44, 0x20000
	s_subb_u32 s45, s45, 0
	s_sub_u32 s14, s14, 0x20000
	s_subb_u32 s15, s15, 0
	s_add_i32 s16, s41, 0xfffff000
	v_lshl_add_u64 v[80:81], s[44:45], 0, v[128:129]
	s_add_i32 s23, s16, 0x4000
	s_mov_b32 m0, s23
	s_nop 0
	global_load_lds_dwordx4 v[80:81], off
	v_lshl_add_u64 v[80:81], s[44:45], 0, v[192:193]
	s_add_i32 s23, s16, 0x6000
	s_mov_b32 m0, s23
	s_nop 0
	global_load_lds_dwordx4 v[80:81], off
	v_lshl_add_u64 v[80:81], s[14:15], 0, v[190:191]
	s_add_i32 s23, s16, 0xc000
	s_mov_b32 m0, s23
	s_nop 0
	global_load_lds_dwordx4 v[80:81], off
	v_lshl_add_u64 v[80:81], s[14:15], 0, v[188:189]
	s_add_i32 s23, s16, 0xe000
	s_mov_b32 m0, s23
	s_nop 0
	global_load_lds_dwordx4 v[80:81], off
	s_lshl_b64 s[14:15], s[50:51], 7
	s_sub_u32 s14, s14, 0x1000
	s_subb_u32 s15, s15, 0
	v_lshl_add_u64 v[80:81], v[194:195], 0, s[14:15]
	s_add_i32 s23, s16, 0x12800
	s_mov_b32 m0, s23
	s_nop 0
	global_load_lds_dwordx4 v[80:81], off

.LBB0_830:
	s_nop 2
	v_max_f32_e32 v80, v113, v113
	v_max_f32_e32 v81, v112, v112
	v_max_f32_e32 v80, v81, v80
	v_max3_f32 v80, v80, v114, v115
	v_max3_f32 v80, v80, v116, v117
	v_max3_f32 v80, v80, v118, v119
	v_max3_f32 v80, v80, v120, v121
	v_max3_f32 v80, v80, v122, v123
	v_max3_f32 v80, v80, v124, v125
	v_max3_f32 v80, v80, v126, v127
	v_max3_f32 v80, v80, v96, v97
	v_max3_f32 v80, v80, v98, v99
	v_max3_f32 v80, v80, v100, v101
	v_max3_f32 v80, v80, v102, v103
	v_max3_f32 v80, v80, v104, v105
	v_max3_f32 v80, v80, v106, v107
	v_max3_f32 v80, v80, v108, v109
	v_max3_f32 v80, v80, v110, v111
	v_mov_b32_e32 v81, v80
	s_nop 1
	v_permlane32_swap_b32_e32 v80, v81
	v_max_f32_e32 v81, v81, v81
	v_max_f32_e32 v80, v80, v80
	s_cmp_lg_u32 s5, 0
	v_max_f32_e32 v80, v80, v81
	s_cbranch_scc0 .LBB0_835
	v_cmp_ge_f32_e32 vcc, s36, v80
	s_cmp_lg_u64 vcc, exec
	s_mov_b64 s[86:87], 0
	s_mov_b64 s[84:85], 0
	s_cbranch_scc1 .LBB0_836
	v_mov_b64_e32 v[94:95], v[78:79]
	v_mov_b32_e32 v231, 1.0
	v_mov_b64_e32 v[92:93], v[76:77]
	v_mov_b64_e32 v[90:91], v[74:75]
	v_mov_b64_e32 v[88:89], v[72:73]
	v_mov_b64_e32 v[86:87], v[70:71]
	v_mov_b64_e32 v[84:85], v[68:69]
	v_mov_b64_e32 v[82:83], v[66:67]
	v_mov_b64_e32 v[80:81], v[64:65]
	s_branch .LBB0_842

.LBB0_842:
	v_exp_f32_e32 v178, v112
	v_exp_f32_e32 v179, v113
	v_exp_f32_e32 v114, v114
	v_exp_f32_e32 v115, v115
	v_exp_f32_e32 v116, v116
	v_exp_f32_e32 v180, v96
	v_add_f32_e32 v96, 0, v178
	v_exp_f32_e32 v117, v117
	v_add_f32_e32 v96, v179, v96
	v_exp_f32_e32 v118, v118
	v_add_f32_e32 v96, v114, v96
	v_exp_f32_e32 v119, v119
	v_add_f32_e32 v96, v115, v96
	v_exp_f32_e32 v120, v120
	v_add_f32_e32 v96, v116, v96
	v_exp_f32_e32 v121, v121
	v_add_f32_e32 v96, v117, v96
	v_exp_f32_e32 v122, v122
	v_add_f32_e32 v96, v118, v96
	v_exp_f32_e32 v123, v123
	v_add_f32_e32 v96, v119, v96
	v_exp_f32_e32 v124, v124
	v_add_f32_e32 v96, v120, v96
	v_exp_f32_e32 v125, v125
	v_add_f32_e32 v96, v121, v96
	v_exp_f32_e32 v126, v126
	v_add_f32_e32 v96, v122, v96
	v_exp_f32_e32 v127, v127
	v_add_f32_e32 v96, v123, v96
	v_add_f32_e32 v96, v124, v96
	v_exp_f32_e32 v181, v97
	v_add_f32_e32 v96, v125, v96
	v_exp_f32_e32 v232, v98
	v_add_f32_e32 v96, v126, v96
	v_exp_f32_e32 v233, v99
	v_add_f32_e32 v96, v127, v96
	v_exp_f32_e32 v234, v100
	v_add_f32_e32 v96, v180, v96
	v_exp_f32_e32 v235, v101
	v_add_f32_e32 v96, v181, v96
	v_exp_f32_e32 v236, v102
	v_add_f32_e32 v96, v232, v96
	v_exp_f32_e32 v237, v103
	v_add_f32_e32 v96, v233, v96
	v_exp_f32_e32 v238, v104
	v_add_f32_e32 v96, v234, v96
	v_exp_f32_e32 v239, v105
	v_add_f32_e32 v96, v235, v96
	v_exp_f32_e32 v240, v106
	v_add_f32_e32 v96, v236, v96
	v_exp_f32_e32 v241, v107
	v_add_f32_e32 v96, v237, v96
	v_exp_f32_e32 v242, v108
	v_add_f32_e32 v96, v238, v96
	v_exp_f32_e32 v243, v109
	v_add_f32_e32 v96, v239, v96
	v_exp_f32_e32 v244, v110
	v_add_f32_e32 v96, v240, v96
	v_exp_f32_e32 v111, v111
	v_add_f32_e32 v96, v241, v96
	v_add_f32_e32 v96, v242, v96
	v_add_f32_e32 v96, v243, v96
	v_add_f32_e32 v96, v244, v96
	v_add_f32_e32 v112, v111, v96
	v_mov_b32_e32 v113, v112
	s_nop 1
	v_permlane32_swap_b32_e32 v112, v113
	v_cvt_pk_bf16_f32 v96, v178, v179
	v_cvt_pk_bf16_f32 v97, v114, v115
	v_cvt_pk_bf16_f32 v98, v116, v117
	v_cvt_pk_bf16_f32 v99, v118, v119
	v_cvt_pk_bf16_f32 v100, v120, v121
	v_cvt_pk_bf16_f32 v101, v122, v123
	v_cvt_pk_bf16_f32 v102, v124, v125
	v_cvt_pk_bf16_f32 v103, v126, v127
	v_cvt_pk_bf16_f32 v104, v180, v181
	v_cvt_pk_bf16_f32 v105, v232, v233
	v_cvt_pk_bf16_f32 v106, v234, v235
	v_cvt_pk_bf16_f32 v107, v236, v237
	v_cvt_pk_bf16_f32 v108, v238, v239
	v_cvt_pk_bf16_f32 v109, v240, v241
	v_cvt_pk_bf16_f32 v110, v242, v243
	v_cvt_pk_bf16_f32 v111, v244, v111
	s_nop 0
	v_permlane32_swap_b32_e32 v96, v98
	v_permlane32_swap_b32_e32 v97, v99
	v_permlane32_swap_b32_e32 v100, v102
	v_permlane32_swap_b32_e32 v101, v103
	v_permlane32_swap_b32_e32 v104, v106
	v_permlane32_swap_b32_e32 v105, v107
	v_permlane32_swap_b32_e32 v108, v110
	v_permlane32_swap_b32_e32 v109, v111
	ds_read_b64_tr_b16 v[114:115], v185 offset:0
	ds_read_b64_tr_b16 v[116:117], v185 offset:0x800
	ds_read_b64_tr_b16 v[118:119], v185 offset:0x1000
	ds_read_b64_tr_b16 v[120:121], v185 offset:0x1800
	ds_read_b64_tr_b16 v[122:123], v185 offset:0x2000
	ds_read_b64_tr_b16 v[124:125], v185 offset:0x2800
	ds_read_b64_tr_b16 v[232:233], v185 offset:0x3000
	ds_read_b64_tr_b16 v[234:235], v185 offset:0x3800
	ds_read_b64_tr_b16 v[236:237], v185 offset:0x200
	ds_read_b64_tr_b16 v[238:239], v185 offset:0xa00
	ds_read_b64_tr_b16 v[240:241], v185 offset:0x1200
	ds_read_b64_tr_b16 v[242:243], v185 offset:0x1a00
	ds_read_b64_tr_b16 v[244:245], v185 offset:0x2200
	ds_read_b64_tr_b16 v[246:247], v185 offset:0x2a00
	ds_read_b64_tr_b16 v[248:249], v185 offset:0x3200
	ds_read_b64_tr_b16 v[250:251], v185 offset:0x3a00
	s_waitcnt lgkmcnt(8)
	s_setprio 1
	v_mfma_f32_32x32x16_bf16 v[16:31], v[96:99], v[114:117], v[16:31]
	v_mfma_f32_32x32x16_bf16 v[16:31], v[100:103], v[118:121], v[16:31]
	v_mfma_f32_32x32x16_bf16 v[16:31], v[104:107], v[122:125], v[16:31]
	v_mfma_f32_32x32x16_bf16 v[16:31], v[108:111], v[232:235], v[16:31]
	s_setprio 0
	ds_read_b64_tr_b16 v[114:115], v185 offset:0x400
	ds_read_b64_tr_b16 v[116:117], v185 offset:0xc00
	ds_read_b64_tr_b16 v[118:119], v185 offset:0x1400
	ds_read_b64_tr_b16 v[120:121], v185 offset:0x1c00
	ds_read_b64_tr_b16 v[122:123], v185 offset:0x2400
	ds_read_b64_tr_b16 v[124:125], v185 offset:0x2c00
	ds_read_b64_tr_b16 v[232:233], v185 offset:0x3400
	ds_read_b64_tr_b16 v[234:235], v185 offset:0x3c00
	s_waitcnt lgkmcnt(8)
	s_setprio 1
	v_mfma_f32_32x32x16_bf16 v[48:63], v[96:99], v[236:239], v[48:63]
	v_mfma_f32_32x32x16_bf16 v[48:63], v[100:103], v[240:243], v[48:63]
	v_mfma_f32_32x32x16_bf16 v[48:63], v[104:107], v[244:247], v[48:63]
	v_mfma_f32_32x32x16_bf16 v[48:63], v[108:111], v[248:251], v[48:63]
	s_setprio 0
	ds_read_b64_tr_b16 v[236:237], v185 offset:0x600
	ds_read_b64_tr_b16 v[238:239], v185 offset:0xe00
	ds_read_b64_tr_b16 v[240:241], v185 offset:0x1600
	ds_read_b64_tr_b16 v[242:243], v185 offset:0x1e00
	ds_read_b64_tr_b16 v[244:245], v185 offset:0x2600
	ds_read_b64_tr_b16 v[246:247], v185 offset:0x2e00
	ds_read_b64_tr_b16 v[248:249], v185 offset:0x3600
	ds_read_b64_tr_b16 v[250:251], v185 offset:0x3e00
	s_waitcnt lgkmcnt(8)
	s_setprio 1
	v_mfma_f32_32x32x16_bf16 v[32:47], v[96:99], v[114:117], v[32:47]
	v_mfma_f32_32x32x16_bf16 v[32:47], v[100:103], v[118:121], v[32:47]
	v_mfma_f32_32x32x16_bf16 v[32:47], v[104:107], v[122:125], v[32:47]
	v_mfma_f32_32x32x16_bf16 v[32:47], v[108:111], v[232:235], v[32:47]
	s_setprio 0
	s_waitcnt lgkmcnt(0)
	s_setprio 1
	v_mfma_f32_32x32x16_bf16 v[0:15], v[96:99], v[236:239], v[0:15]
	v_mfma_f32_32x32x16_bf16 v[0:15], v[100:103], v[240:243], v[0:15]
	v_mfma_f32_32x32x16_bf16 v[0:15], v[104:107], v[244:247], v[0:15]
	v_mfma_f32_32x32x16_bf16 v[0:15], v[108:111], v[248:251], v[0:15]
	s_setprio 0
	s_waitcnt vmcnt(0)
	s_add_i32 s5, s5, 2
	s_cmp_ge_i32 s5, s13
	s_barrier
	s_cbranch_scc1 .LBB0_844
	s_cmp_lt_u32 s3, 0x100
	s_cbranch_scc1 .LBB0_844
	s_mov_b32 s83, s51
	s_lshl_b64 s[14:15], s[82:83], 13
	s_add_u32 s44, s80, s14
	s_addc_u32 s45, s81, s15
	s_add_u32 s14, s78, s14
	s_addc_u32 s15, s79, s15
	v_lshl_add_u64 v[96:97], s[44:45], 0, v[128:129]
	s_mov_b32 m0, s97
	s_nop 0
	global_load_lds_dwordx4 v[96:97], off
	s_cmp_lg_u32 0, -1
	s_cselect_b32 s16, 0, 0
	s_add_i32 s16, s16, s41
	v_lshl_add_u64 v[96:97], s[44:45], 0, v[192:193]
	s_add_i32 s23, s16, 0x2000
	s_mov_b32 m0, s23
	s_nop 0
	global_load_lds_dwordx4 v[96:97], off
	v_lshl_add_u64 v[96:97], s[14:15], 0, v[190:191]
	s_mov_b32 m0, s40
	s_nop 0
	global_load_lds_dwordx4 v[96:97], off
	v_lshl_add_u64 v[96:97], s[14:15], 0, v[188:189]
	s_add_i32 s16, s16, 0xa000
	s_mov_b32 m0, s16
	s_nop 0
	global_load_lds_dwordx4 v[96:97], off
	s_lshl_b64 s[14:15], s[82:83], 7
	v_lshl_add_u64 v[96:97], v[194:195], 0, s[14:15]
	s_mov_b32 m0, s46
	s_nop 0
	global_load_lds_dwordx4 v[96:97], off
	s_lshl_b64 s[14:15], s[82:83], 13
	s_add_u32 s44, s80, s14
	s_addc_u32 s45, s81, s15
	s_add_u32 s14, s78, s14
	s_addc_u32 s15, s79, s15
	s_sub_u32 s44, s44, 0x20000
	s_subb_u32 s45, s45, 0
	s_sub_u32 s14, s14, 0x20000
	s_subb_u32 s15, s15, 0
	s_add_i32 s16, s41, 0xfffff000
	v_lshl_add_u64 v[96:97], s[44:45], 0, v[128:129]
	s_add_i32 s23, s97, 0xfffff000
	s_mov_b32 m0, s23
	s_nop 0
	global_load_lds_dwordx4 v[96:97], off
	v_lshl_add_u64 v[96:97], s[44:45], 0, v[192:193]
	s_add_i32 s23, s16, 0x2000
	s_mov_b32 m0, s23
	s_nop 0
	global_load_lds_dwordx4 v[96:97], off
	v_lshl_add_u64 v[96:97], s[14:15], 0, v[190:191]
	s_add_i32 s23, s40, 0xfffff000
	s_mov_b32 m0, s23
	s_nop 0
	global_load_lds_dwordx4 v[96:97], off
	v_lshl_add_u64 v[96:97], s[14:15], 0, v[188:189]
	s_add_i32 s23, s16, 0xa000
	s_mov_b32 m0, s23
	s_nop 0
	global_load_lds_dwordx4 v[96:97], off
	s_lshl_b64 s[14:15], s[82:83], 7
	s_sub_u32 s14, s14, 0x1000
	s_subb_u32 s15, s15, 0
	v_lshl_add_u64 v[96:97], v[194:195], 0, s[14:15]
	s_add_i32 s23, s46, 0xfffff000
	s_mov_b32 m0, s23
	s_nop 0
	global_load_lds_dwordx4 v[96:97], off
